# gemm_sample_rows inner K loop hand-pipelined: fragment loads issued 3 steps ahead in 3 register sets (phases 3 and 8)
# baseline (speedup 1.0000x reference)
; template <int NH>
; __device__ void gemm_sample_rows(const Params& p, const u16* __restrict__ A, const u16* __restrict__ Bt,
;                                  const float* __restrict__ resid, float* __restrict__ outf, unsigned char* smem, const int rep) {
;     ...
; #pragma unroll 2
;     for (int ks = 0; ks < 8; ++ks) {
;       bf16x8 af[4], bfr[4];
; #pragma unroll
;       for (int mf = 0; mf < 4; ++mf) af[mf] = *(const bf16x8*)(ap + (size_t)(mf * 16) * K + ks * 32);
; #pragma unroll
;       for (int nf = 0; nf < 4; ++nf) bfr[nf] = *(const bf16x8*)(bp + (size_t)(nf * 16) * K + ks * 32);
; #pragma unroll
;       for (int mf = 0; mf < 4; ++mf)
; #pragma unroll
;         for (int nf = 0; nf < 4; ++nf)
;           acc[mf][nf] = __builtin_amdgcn_mfma_f32_16x16x32_bf16(af[mf], bfr[nf], acc[mf][nf], 0, 0, 0);
;     }
.LBB0_730:
	v_add_co_u32_e64 v200, s[2:3], s21, v66
	s_nop 1
	v_addc_co_u32_e64 v201, s[2:3], 0, v67, s[2:3]
	v_add_co_u32_e64 v202, s[2:3], s22, v66
	s_nop 1
	v_addc_co_u32_e64 v203, s[2:3], 0, v67, s[2:3]
	v_add_co_u32_e64 v204, s[2:3], s23, v66
	s_nop 1
	v_addc_co_u32_e64 v205, s[2:3], 0, v67, s[2:3]
	v_add_co_u32_e64 v206, s[2:3], s24, v66
	s_nop 1
	v_addc_co_u32_e64 v207, s[2:3], 0, v67, s[2:3]
	v_add_co_u32_e64 v208, s[2:3], s25, v68
	s_nop 1
	v_addc_co_u32_e64 v209, s[2:3], 0, v69, s[2:3]
	v_add_co_u32_e64 v210, s[2:3], s26, v68
	s_nop 1
	v_addc_co_u32_e64 v211, s[2:3], 0, v69, s[2:3]
	v_add_co_u32_e64 v212, s[2:3], s27, v68
	s_nop 1
	v_addc_co_u32_e64 v213, s[2:3], 0, v69, s[2:3]
	v_add_co_u32_e64 v214, s[2:3], s28, v68
	s_nop 1
	v_addc_co_u32_e64 v215, s[2:3], 0, v69, s[2:3]
	global_load_dwordx4 v[124:127], v[200:201], off
	global_load_dwordx4 v[128:131], v[202:203], off
	global_load_dwordx4 v[132:135], v[204:205], off
	global_load_dwordx4 v[136:139], v[206:207], off
	global_load_dwordx4 v[140:143], v[208:209], off
	global_load_dwordx4 v[144:147], v[210:211], off
	global_load_dwordx4 v[148:151], v[212:213], off
	global_load_dwordx4 v[152:155], v[214:215], off
	global_load_dwordx4 v[216:219], v[200:201], off offset:64
	global_load_dwordx4 v[220:223], v[202:203], off offset:64
	global_load_dwordx4 v[224:227], v[204:205], off offset:64
	global_load_dwordx4 v[228:231], v[206:207], off offset:64
	global_load_dwordx4 v[232:235], v[208:209], off offset:64
	global_load_dwordx4 v[236:239], v[210:211], off offset:64
	global_load_dwordx4 v[240:243], v[212:213], off offset:64
	global_load_dwordx4 v[244:247], v[214:215], off offset:64
	global_load_dwordx4 v[156:159], v[200:201], off offset:128
	global_load_dwordx4 v[160:163], v[202:203], off offset:128
	global_load_dwordx4 v[164:167], v[204:205], off offset:128
	global_load_dwordx4 v[168:171], v[206:207], off offset:128
	global_load_dwordx4 v[172:175], v[208:209], off offset:128
	global_load_dwordx4 v[176:179], v[210:211], off offset:128
	global_load_dwordx4 v[182:185], v[212:213], off offset:128
	global_load_dwordx4 v[186:189], v[214:215], off offset:128
	s_waitcnt vmcnt(16)
	v_mfma_f32_16x16x32_bf16 v[60:63], v[124:127], v[140:143], v[60:63]
	v_mfma_f32_16x16x32_bf16 v[52:55], v[124:127], v[144:147], v[52:55]
	v_mfma_f32_16x16x32_bf16 v[48:51], v[124:127], v[148:151], v[48:51]
	v_mfma_f32_16x16x32_bf16 v[44:47], v[124:127], v[152:155], v[44:47]
	v_mfma_f32_16x16x32_bf16 v[40:43], v[128:131], v[140:143], v[40:43]
	v_mfma_f32_16x16x32_bf16 v[36:39], v[128:131], v[144:147], v[36:39]
	v_mfma_f32_16x16x32_bf16 v[20:23], v[128:131], v[148:151], v[20:23]
	v_mfma_f32_16x16x32_bf16 v[12:15], v[128:131], v[152:155], v[12:15]
	v_mfma_f32_16x16x32_bf16 v[16:19], v[132:135], v[140:143], v[16:19]
	v_mfma_f32_16x16x32_bf16 v[24:27], v[132:135], v[144:147], v[24:27]
	v_mfma_f32_16x16x32_bf16 v[28:31], v[132:135], v[148:151], v[28:31]
	v_mfma_f32_16x16x32_bf16 v[32:35], v[132:135], v[152:155], v[32:35]
	v_mfma_f32_16x16x32_bf16 v[0:3], v[136:139], v[140:143], v[0:3]
	v_mfma_f32_16x16x32_bf16 v[4:7], v[136:139], v[144:147], v[4:7]
	v_mfma_f32_16x16x32_bf16 v[8:11], v[136:139], v[148:151], v[8:11]
	v_mfma_f32_16x16x32_bf16 v[56:59], v[136:139], v[152:155], v[56:59]
	global_load_dwordx4 v[124:127], v[200:201], off offset:192
	global_load_dwordx4 v[128:131], v[202:203], off offset:192
	global_load_dwordx4 v[132:135], v[204:205], off offset:192
	global_load_dwordx4 v[136:139], v[206:207], off offset:192
	global_load_dwordx4 v[140:143], v[208:209], off offset:192
	global_load_dwordx4 v[144:147], v[210:211], off offset:192
	global_load_dwordx4 v[148:151], v[212:213], off offset:192
	global_load_dwordx4 v[152:155], v[214:215], off offset:192
	s_waitcnt vmcnt(16)
	v_mfma_f32_16x16x32_bf16 v[60:63], v[216:219], v[232:235], v[60:63]
	v_mfma_f32_16x16x32_bf16 v[52:55], v[216:219], v[236:239], v[52:55]
	v_mfma_f32_16x16x32_bf16 v[48:51], v[216:219], v[240:243], v[48:51]
	v_mfma_f32_16x16x32_bf16 v[44:47], v[216:219], v[244:247], v[44:47]
	v_mfma_f32_16x16x32_bf16 v[40:43], v[220:223], v[232:235], v[40:43]
	v_mfma_f32_16x16x32_bf16 v[36:39], v[220:223], v[236:239], v[36:39]
	v_mfma_f32_16x16x32_bf16 v[20:23], v[220:223], v[240:243], v[20:23]
	v_mfma_f32_16x16x32_bf16 v[12:15], v[220:223], v[244:247], v[12:15]
	v_mfma_f32_16x16x32_bf16 v[16:19], v[224:227], v[232:235], v[16:19]
	v_mfma_f32_16x16x32_bf16 v[24:27], v[224:227], v[236:239], v[24:27]
	v_mfma_f32_16x16x32_bf16 v[28:31], v[224:227], v[240:243], v[28:31]
	v_mfma_f32_16x16x32_bf16 v[32:35], v[224:227], v[244:247], v[32:35]
	v_mfma_f32_16x16x32_bf16 v[0:3], v[228:231], v[232:235], v[0:3]
	v_mfma_f32_16x16x32_bf16 v[4:7], v[228:231], v[236:239], v[4:7]
	v_mfma_f32_16x16x32_bf16 v[8:11], v[228:231], v[240:243], v[8:11]
	v_mfma_f32_16x16x32_bf16 v[56:59], v[228:231], v[244:247], v[56:59]
	global_load_dwordx4 v[216:219], v[200:201], off offset:256
	global_load_dwordx4 v[220:223], v[202:203], off offset:256
	global_load_dwordx4 v[224:227], v[204:205], off offset:256
	global_load_dwordx4 v[228:231], v[206:207], off offset:256
	global_load_dwordx4 v[232:235], v[208:209], off offset:256
	global_load_dwordx4 v[236:239], v[210:211], off offset:256
	global_load_dwordx4 v[240:243], v[212:213], off offset:256
	global_load_dwordx4 v[244:247], v[214:215], off offset:256
	s_waitcnt vmcnt(16)
; template <int NH>
; __device__ void gemm_sample_rows(const Params& p, const u16* __restrict__ A, const u16* __restrict__ Bt,
;                                  const float* __restrict__ resid, float* __restrict__ outf, unsigned char* smem, const int rep) {
;     ...
; #pragma unroll 2
;     for (int ks = 0; ks < 8; ++ks) {
;       bf16x8 af[4], bfr[4];
; #pragma unroll
;       for (int mf = 0; mf < 4; ++mf) af[mf] = *(const bf16x8*)(ap + (size_t)(mf * 16) * K + ks * 32);
; #pragma unroll
;       for (int nf = 0; nf < 4; ++nf) bfr[nf] = *(const bf16x8*)(bp + (size_t)(nf * 16) * K + ks * 32);
; #pragma unroll
;       for (int mf = 0; mf < 4; ++mf)
; #pragma unroll
;         for (int nf = 0; nf < 4; ++nf)
;           acc[mf][nf] = __builtin_amdgcn_mfma_f32_16x16x32_bf16(af[mf], bfr[nf], acc[mf][nf], 0, 0, 0);
;     }
	v_mfma_f32_16x16x32_bf16 v[60:63], v[156:159], v[172:175], v[60:63]
	v_mfma_f32_16x16x32_bf16 v[52:55], v[156:159], v[176:179], v[52:55]
	v_mfma_f32_16x16x32_bf16 v[48:51], v[156:159], v[182:185], v[48:51]
	v_mfma_f32_16x16x32_bf16 v[44:47], v[156:159], v[186:189], v[44:47]
	v_mfma_f32_16x16x32_bf16 v[40:43], v[160:163], v[172:175], v[40:43]
	v_mfma_f32_16x16x32_bf16 v[36:39], v[160:163], v[176:179], v[36:39]
	v_mfma_f32_16x16x32_bf16 v[20:23], v[160:163], v[182:185], v[20:23]
	v_mfma_f32_16x16x32_bf16 v[12:15], v[160:163], v[186:189], v[12:15]
	v_mfma_f32_16x16x32_bf16 v[16:19], v[164:167], v[172:175], v[16:19]
	v_mfma_f32_16x16x32_bf16 v[24:27], v[164:167], v[176:179], v[24:27]
	v_mfma_f32_16x16x32_bf16 v[28:31], v[164:167], v[182:185], v[28:31]
	v_mfma_f32_16x16x32_bf16 v[32:35], v[164:167], v[186:189], v[32:35]
	v_mfma_f32_16x16x32_bf16 v[0:3], v[168:171], v[172:175], v[0:3]
	v_mfma_f32_16x16x32_bf16 v[4:7], v[168:171], v[176:179], v[4:7]
	v_mfma_f32_16x16x32_bf16 v[8:11], v[168:171], v[182:185], v[8:11]
	v_mfma_f32_16x16x32_bf16 v[56:59], v[168:171], v[186:189], v[56:59]
	global_load_dwordx4 v[156:159], v[200:201], off offset:320
	global_load_dwordx4 v[160:163], v[202:203], off offset:320
	global_load_dwordx4 v[164:167], v[204:205], off offset:320
	global_load_dwordx4 v[168:171], v[206:207], off offset:320
	global_load_dwordx4 v[172:175], v[208:209], off offset:320
	global_load_dwordx4 v[176:179], v[210:211], off offset:320
	global_load_dwordx4 v[182:185], v[212:213], off offset:320
	global_load_dwordx4 v[186:189], v[214:215], off offset:320
	s_waitcnt vmcnt(16)
	v_mfma_f32_16x16x32_bf16 v[60:63], v[124:127], v[140:143], v[60:63]
	v_mfma_f32_16x16x32_bf16 v[52:55], v[124:127], v[144:147], v[52:55]
	v_mfma_f32_16x16x32_bf16 v[48:51], v[124:127], v[148:151], v[48:51]
	v_mfma_f32_16x16x32_bf16 v[44:47], v[124:127], v[152:155], v[44:47]
	v_mfma_f32_16x16x32_bf16 v[40:43], v[128:131], v[140:143], v[40:43]
	v_mfma_f32_16x16x32_bf16 v[36:39], v[128:131], v[144:147], v[36:39]
	v_mfma_f32_16x16x32_bf16 v[20:23], v[128:131], v[148:151], v[20:23]
	v_mfma_f32_16x16x32_bf16 v[12:15], v[128:131], v[152:155], v[12:15]
	v_mfma_f32_16x16x32_bf16 v[16:19], v[132:135], v[140:143], v[16:19]
	v_mfma_f32_16x16x32_bf16 v[24:27], v[132:135], v[144:147], v[24:27]
	v_mfma_f32_16x16x32_bf16 v[28:31], v[132:135], v[148:151], v[28:31]
	v_mfma_f32_16x16x32_bf16 v[32:35], v[132:135], v[152:155], v[32:35]
	v_mfma_f32_16x16x32_bf16 v[0:3], v[136:139], v[140:143], v[0:3]
	v_mfma_f32_16x16x32_bf16 v[4:7], v[136:139], v[144:147], v[4:7]
	v_mfma_f32_16x16x32_bf16 v[8:11], v[136:139], v[148:151], v[8:11]
	v_mfma_f32_16x16x32_bf16 v[56:59], v[136:139], v[152:155], v[56:59]
	global_load_dwordx4 v[124:127], v[200:201], off offset:384
	global_load_dwordx4 v[128:131], v[202:203], off offset:384
	global_load_dwordx4 v[132:135], v[204:205], off offset:384
	global_load_dwordx4 v[136:139], v[206:207], off offset:384
	global_load_dwordx4 v[140:143], v[208:209], off offset:384
	global_load_dwordx4 v[144:147], v[210:211], off offset:384
	global_load_dwordx4 v[148:151], v[212:213], off offset:384
	global_load_dwordx4 v[152:155], v[214:215], off offset:384
	s_waitcnt vmcnt(16)
	v_mfma_f32_16x16x32_bf16 v[60:63], v[216:219], v[232:235], v[60:63]
	v_mfma_f32_16x16x32_bf16 v[52:55], v[216:219], v[236:239], v[52:55]
	v_mfma_f32_16x16x32_bf16 v[48:51], v[216:219], v[240:243], v[48:51]
	v_mfma_f32_16x16x32_bf16 v[44:47], v[216:219], v[244:247], v[44:47]
	v_mfma_f32_16x16x32_bf16 v[40:43], v[220:223], v[232:235], v[40:43]
	v_mfma_f32_16x16x32_bf16 v[36:39], v[220:223], v[236:239], v[36:39]
	v_mfma_f32_16x16x32_bf16 v[20:23], v[220:223], v[240:243], v[20:23]
	v_mfma_f32_16x16x32_bf16 v[12:15], v[220:223], v[244:247], v[12:15]
	v_mfma_f32_16x16x32_bf16 v[16:19], v[224:227], v[232:235], v[16:19]
	v_mfma_f32_16x16x32_bf16 v[24:27], v[224:227], v[236:239], v[24:27]
	v_mfma_f32_16x16x32_bf16 v[28:31], v[224:227], v[240:243], v[28:31]
	v_mfma_f32_16x16x32_bf16 v[32:35], v[224:227], v[244:247], v[32:35]
	v_mfma_f32_16x16x32_bf16 v[0:3], v[228:231], v[232:235], v[0:3]
	v_mfma_f32_16x16x32_bf16 v[4:7], v[228:231], v[236:239], v[4:7]
	v_mfma_f32_16x16x32_bf16 v[8:11], v[228:231], v[240:243], v[8:11]
	v_mfma_f32_16x16x32_bf16 v[56:59], v[228:231], v[244:247], v[56:59]
	global_load_dwordx4 v[216:219], v[200:201], off offset:448
	global_load_dwordx4 v[220:223], v[202:203], off offset:448
	global_load_dwordx4 v[224:227], v[204:205], off offset:448
	global_load_dwordx4 v[228:231], v[206:207], off offset:448
	global_load_dwordx4 v[232:235], v[208:209], off offset:448
	global_load_dwordx4 v[236:239], v[210:211], off offset:448
	global_load_dwordx4 v[240:243], v[212:213], off offset:448
	global_load_dwordx4 v[244:247], v[214:215], off offset:448
	s_waitcnt vmcnt(16)
	v_mfma_f32_16x16x32_bf16 v[60:63], v[156:159], v[172:175], v[60:63]
	v_mfma_f32_16x16x32_bf16 v[52:55], v[156:159], v[176:179], v[52:55]
	v_mfma_f32_16x16x32_bf16 v[48:51], v[156:159], v[182:185], v[48:51]
	v_mfma_f32_16x16x32_bf16 v[44:47], v[156:159], v[186:189], v[44:47]
	v_mfma_f32_16x16x32_bf16 v[40:43], v[160:163], v[172:175], v[40:43]
	v_mfma_f32_16x16x32_bf16 v[36:39], v[160:163], v[176:179], v[36:39]
	v_mfma_f32_16x16x32_bf16 v[20:23], v[160:163], v[182:185], v[20:23]
	v_mfma_f32_16x16x32_bf16 v[12:15], v[160:163], v[186:189], v[12:15]
	v_mfma_f32_16x16x32_bf16 v[16:19], v[164:167], v[172:175], v[16:19]
	v_mfma_f32_16x16x32_bf16 v[24:27], v[164:167], v[176:179], v[24:27]
	v_mfma_f32_16x16x32_bf16 v[28:31], v[164:167], v[182:185], v[28:31]
	v_mfma_f32_16x16x32_bf16 v[32:35], v[164:167], v[186:189], v[32:35]
	v_mfma_f32_16x16x32_bf16 v[0:3], v[168:171], v[172:175], v[0:3]
	v_mfma_f32_16x16x32_bf16 v[4:7], v[168:171], v[176:179], v[4:7]
	v_mfma_f32_16x16x32_bf16 v[8:11], v[168:171], v[182:185], v[8:11]
	v_mfma_f32_16x16x32_bf16 v[56:59], v[168:171], v[186:189], v[56:59]
	s_waitcnt vmcnt(8)
; template <int NH>
; __device__ void gemm_sample_rows(const Params& p, const u16* __restrict__ A, const u16* __restrict__ Bt,
;                                  const float* __restrict__ resid, float* __restrict__ outf, unsigned char* smem, const int rep) {
;     ...
; #pragma unroll
;       for (int mf = 0; mf < 4; ++mf)
; #pragma unroll
;         for (int nf = 0; nf < 4; ++nf)
;           acc[mf][nf] = __builtin_amdgcn_mfma_f32_16x16x32_bf16(af[mf], bfr[nf], acc[mf][nf], 0, 0, 0);
;     }
;     __syncthreads();
;     {
;       const int h = (w * 256) / (K / NH);
; #pragma unroll
;       for (int mf = 0; mf < 4; ++mf)
; #pragma unroll
;         for (int r = 0; r < 4; ++r) {
;           const int row = mf * 16 + 4 * g + r;
;           const float sc = rstdS[row * NH + h];
; #pragma unroll
;           for (int nf = 0; nf < 4; ++nf) red[(w * 64 + row) * RS + nf * 16 + l15] = acc[mf][nf][r] * sc;
;         }
;     }
	v_mfma_f32_16x16x32_bf16 v[60:63], v[124:127], v[140:143], v[60:63]
	v_mfma_f32_16x16x32_bf16 v[52:55], v[124:127], v[144:147], v[52:55]
	v_mfma_f32_16x16x32_bf16 v[48:51], v[124:127], v[148:151], v[48:51]
	v_mfma_f32_16x16x32_bf16 v[44:47], v[124:127], v[152:155], v[44:47]
	v_mfma_f32_16x16x32_bf16 v[40:43], v[128:131], v[140:143], v[40:43]
	v_mfma_f32_16x16x32_bf16 v[36:39], v[128:131], v[144:147], v[36:39]
	v_mfma_f32_16x16x32_bf16 v[20:23], v[128:131], v[148:151], v[20:23]
	v_mfma_f32_16x16x32_bf16 v[12:15], v[128:131], v[152:155], v[12:15]
	v_mfma_f32_16x16x32_bf16 v[16:19], v[132:135], v[140:143], v[16:19]
	v_mfma_f32_16x16x32_bf16 v[24:27], v[132:135], v[144:147], v[24:27]
	v_mfma_f32_16x16x32_bf16 v[28:31], v[132:135], v[148:151], v[28:31]
	v_mfma_f32_16x16x32_bf16 v[32:35], v[132:135], v[152:155], v[32:35]
	v_mfma_f32_16x16x32_bf16 v[0:3], v[136:139], v[140:143], v[0:3]
	v_mfma_f32_16x16x32_bf16 v[4:7], v[136:139], v[144:147], v[4:7]
	v_mfma_f32_16x16x32_bf16 v[8:11], v[136:139], v[148:151], v[8:11]
	v_mfma_f32_16x16x32_bf16 v[56:59], v[136:139], v[152:155], v[56:59]
	s_waitcnt vmcnt(0)
	v_mfma_f32_16x16x32_bf16 v[60:63], v[216:219], v[232:235], v[60:63]
	v_mfma_f32_16x16x32_bf16 v[52:55], v[216:219], v[236:239], v[52:55]
	v_mfma_f32_16x16x32_bf16 v[48:51], v[216:219], v[240:243], v[48:51]
	v_mfma_f32_16x16x32_bf16 v[44:47], v[216:219], v[244:247], v[44:47]
	v_mfma_f32_16x16x32_bf16 v[40:43], v[220:223], v[232:235], v[40:43]
	v_mfma_f32_16x16x32_bf16 v[36:39], v[220:223], v[236:239], v[36:39]
	v_mfma_f32_16x16x32_bf16 v[20:23], v[220:223], v[240:243], v[20:23]
	v_mfma_f32_16x16x32_bf16 v[12:15], v[220:223], v[244:247], v[12:15]
	v_mfma_f32_16x16x32_bf16 v[16:19], v[224:227], v[232:235], v[16:19]
	v_mfma_f32_16x16x32_bf16 v[24:27], v[224:227], v[236:239], v[24:27]
	v_mfma_f32_16x16x32_bf16 v[28:31], v[224:227], v[240:243], v[28:31]
	v_mfma_f32_16x16x32_bf16 v[32:35], v[224:227], v[244:247], v[32:35]
	v_mfma_f32_16x16x32_bf16 v[0:3], v[228:231], v[232:235], v[0:3]
	v_mfma_f32_16x16x32_bf16 v[4:7], v[228:231], v[236:239], v[4:7]
	v_mfma_f32_16x16x32_bf16 v[8:11], v[228:231], v[240:243], v[8:11]
	v_mfma_f32_16x16x32_bf16 v[56:59], v[228:231], v[244:247], v[56:59]
	s_movk_i32 s4, 0x200
	s_mov_b32 s5, 0
	s_waitcnt lgkmcnt(0)
	s_barrier
	ds_read_b32 v66, v90
	s_add_i32 s15, s15, s16
	s_add_i32 s17, s17, s18
	s_waitcnt lgkmcnt(0)
	v_mul_f32_e32 v60, v60, v66
	v_mul_f32_e32 v52, v52, v66
	v_mul_f32_e32 v48, v48, v66
	v_mul_f32_e32 v44, v44, v66
	ds_write2_b32 v91, v60, v52 offset1:16
	ds_write2_b32 v91, v48, v44 offset0:32 offset1:48
	ds_read_b32 v44, v92
	s_waitcnt lgkmcnt(0)
	v_mul_f32_e32 v48, v61, v44
	v_mul_f32_e32 v52, v53, v44
	ds_write2_b32 v93, v48, v52 offset1:16
	v_mul_f32_e32 v48, v49, v44
	v_mul_f32_e32 v44, v45, v44
	ds_write2_b32 v93, v48, v44 offset0:32 offset1:48
	ds_read_b32 v44, v94
	s_waitcnt lgkmcnt(0)
	v_mul_f32_e32 v45, v62, v44
	v_mul_f32_e32 v48, v54, v44
	ds_write2_b32 v95, v45, v48 offset1:16
	v_mul_f32_e32 v45, v50, v44
	v_mul_f32_e32 v44, v46, v44
	ds_write2_b32 v95, v45, v44 offset0:32 offset1:48
	ds_read_b32 v44, v96
	s_waitcnt lgkmcnt(0)
	v_mul_f32_e32 v45, v63, v44
	v_mul_f32_e32 v46, v55, v44
	ds_write2_b32 v97, v45, v46 offset1:16
	v_mul_f32_e32 v45, v51, v44
	v_mul_f32_e32 v44, v47, v44
	ds_write2_b32 v97, v45, v44 offset0:32 offset1:48
	ds_read_b32 v44, v98
	s_waitcnt lgkmcnt(0)
	v_mul_f32_e32 v40, v40, v44
	v_mul_f32_e32 v36, v36, v44
	v_mul_f32_e32 v20, v20, v44
	v_mul_f32_e32 v12, v12, v44
	ds_write2_b32 v99, v40, v36 offset1:16
	ds_write2_b32 v99, v20, v12 offset0:32 offset1:48
	ds_read_b32 v12, v100
	v_add_u32_e32 v40, 0xc318, v70
	s_waitcnt lgkmcnt(0)
	v_mul_f32_e32 v20, v41, v12
	v_mul_f32_e32 v36, v37, v12
	ds_write2_b32 v101, v20, v36 offset1:16
	v_mul_f32_e32 v20, v21, v12
	v_mul_f32_e32 v12, v13, v12
	ds_write2_b32 v101, v20, v12 offset0:32 offset1:48
	ds_read_b32 v12, v102
	v_add_u32_e32 v36, 0x4118, v70
	s_waitcnt lgkmcnt(0)
	v_mul_f32_e32 v13, v42, v12
	v_mul_f32_e32 v20, v38, v12
	ds_write2_b32 v103, v13, v20 offset1:16
	v_mul_f32_e32 v13, v22, v12
	v_mul_f32_e32 v12, v14, v12
	ds_write2_b32 v103, v13, v12 offset0:32 offset1:48
	ds_read_b32 v12, v104
	v_add_u32_e32 v20, 0xc308, v70
	v_add_u32_e32 v22, 0x4110, v70
	v_add_u32_e32 v38, 0x8218, v70
	s_waitcnt lgkmcnt(0)
	v_mul_f32_e32 v13, v43, v12
	v_mul_f32_e32 v14, v39, v12
	ds_write2_b32 v105, v13, v14 offset1:16
	v_mul_f32_e32 v13, v23, v12
	v_mul_f32_e32 v12, v15, v12
	ds_write2_b32 v105, v13, v12 offset0:32 offset1:48
	ds_read_b32 v12, v106
	s_waitcnt lgkmcnt(0)
	v_mul_f32_e32 v13, v16, v12
	v_mul_f32_e32 v14, v24, v12
	ds_write2_b32 v107, v13, v14 offset1:16
	v_mul_f32_e32 v13, v28, v12
	v_mul_f32_e32 v12, v32, v12
	ds_write2_b32 v107, v13, v12 offset0:32 offset1:48
	ds_read_b32 v12, v108
	v_add_u32_e32 v16, 0x4108, v70
	v_add_u32_e32 v24, 0x8210, v70
	s_waitcnt lgkmcnt(0)
	v_mul_f32_e32 v13, v17, v12
	v_mul_f32_e32 v14, v25, v12
	ds_write2_b32 v109, v13, v14 offset1:16
	v_mul_f32_e32 v13, v29, v12
	v_mul_f32_e32 v12, v33, v12
	ds_write2_b32 v109, v13, v12 offset0:32 offset1:48
	ds_read_b32 v12, v110
	s_waitcnt lgkmcnt(0)
	v_mul_f32_e32 v13, v18, v12
	v_mul_f32_e32 v14, v26, v12
	ds_write2_b32 v111, v13, v14 offset1:16
	v_mul_f32_e32 v13, v30, v12
	v_mul_f32_e32 v12, v34, v12
	ds_write2_b32 v111, v13, v12 offset0:32 offset1:48
	ds_read_b32 v12, v112
	v_add_u32_e32 v18, 0x8208, v70
	v_add_u32_e32 v34, 0xc310, v70
	s_waitcnt lgkmcnt(0)
	v_mul_f32_e32 v13, v19, v12
	v_mul_f32_e32 v14, v27, v12
	ds_write2_b32 v113, v13, v14 offset1:16
	v_mul_f32_e32 v13, v31, v12
	v_mul_f32_e32 v12, v35, v12
	ds_write2_b32 v113, v13, v12 offset0:32 offset1:48
	ds_read_b32 v12, v114
	v_add_u32_e32 v14, 0xc300, v70
	s_waitcnt lgkmcnt(0)
	v_mul_f32_e32 v0, v0, v12
	v_mul_f32_e32 v4, v4, v12
	ds_write2_b32 v115, v0, v4 offset1:16
	v_mul_f32_e32 v0, v8, v12
	v_mul_f32_e32 v4, v56, v12
	ds_write2_b32 v115, v0, v4 offset0:32 offset1:48
	ds_read_b32 v0, v116
	v_add_u32_e32 v12, 0x8200, v70
	s_waitcnt lgkmcnt(0)
	v_mul_f32_e32 v1, v1, v0
	v_mul_f32_e32 v4, v5, v0
	ds_write2_b32 v117, v1, v4 offset1:16
	v_mul_f32_e32 v1, v9, v0
	v_mul_f32_e32 v0, v57, v0
	ds_write2_b32 v117, v1, v0 offset0:32 offset1:48
	ds_read_b32 v0, v118
	s_waitcnt lgkmcnt(0)
	v_mul_f32_e32 v1, v2, v0
	v_mul_f32_e32 v2, v6, v0
	ds_write2_b32 v119, v1, v2 offset1:16
	v_mul_f32_e32 v1, v10, v0
	v_mul_f32_e32 v0, v58, v0
	ds_write2_b32 v119, v1, v0 offset0:32 offset1:48
	ds_read_b32 v0, v120
	v_add_u32_e32 v10, 0x4100, v70
	s_waitcnt lgkmcnt(0)
	v_mul_f32_e32 v1, v3, v0
	v_mul_f32_e32 v2, v7, v0
	ds_write2_b32 v121, v1, v2 offset1:16
	v_mul_f32_e32 v1, v11, v0
	v_mul_f32_e32 v0, v59, v0
	ds_write2_b32 v121, v1, v0 offset0:32 offset1:48
	v_add_u32_e32 v0, s0, v197
	v_ashrrev_i32_e32 v1, 31, v0
	v_lshlrev_b64 v[0:1], 12, v[0:1]
	s_lshl_b32 s0, s29, 8
	v_lshl_add_u64 v[0:1], s[10:11], 0, v[0:1]
	s_and_b32 s0, s0, 0xf00
	v_lshl_add_u64 v[0:1], v[0:1], 0, s[0:1]
	v_lshl_add_u64 v[8:9], v[0:1], 0, v[180:181]
	s_waitcnt lgkmcnt(0)
	s_barrier
; template <int NH>
; __device__ void gemm_sample_rows(const Params& p, const u16* __restrict__ A, const u16* __restrict__ Bt,
;                                  const float* __restrict__ resid, float* __restrict__ outf, unsigned char* smem, const int rep) {
;     ...
;     {
;       const int row = tid >> 3, c0 = (tid & 7) * 8;
;       float o[8];
;       const size_t gidx = (size_t)(m0 + row) * 1024 + n0 + c0;
;       const float* rp = resid ? resid + gidx : p.x_sample + (size_t)(m0 - NPROMPT + row) * 1024 + n0 + c0;
;       const float4 r0 = *(const float4*)rp, r1 = *(const float4*)(rp + 4);
;       o[0] = r0.x; o[1] = r0.y; o[2] = r0.z; o[3] = r0.w; o[4] = r1.x; o[5] = r1.y; o[6] = r1.z; o[7] = r1.w;
; #pragma unroll
;       for (int ww = 0; ww < 8; ++ww)
; #pragma unroll
;         for (int j = 0; j < 8; ++j) o[j] += red[(ww * 64 + row) * RS + c0 + j];
;       *(float4*)(outf + gidx) = make_float4(o[0], o[1], o[2], o[3]);
;       *(float4*)(outf + gidx + 4) = make_float4(o[4], o[5], o[6], o[7]);
;     }
;     __syncthreads();
;   }
	global_load_dwordx4 v[0:3], v[8:9], off
	global_load_dwordx4 v[4:7], v[8:9], off offset:16
	ds_read2_b32 v[10:11], v10 offset1:1
	ds_read2_b32 v[12:13], v12 offset1:1
	ds_read2_b32 v[14:15], v14 offset1:1
	ds_read2_b32 v[16:17], v16 offset1:1
	ds_read2_b32 v[18:19], v18 offset1:1
	ds_read2_b32 v[20:21], v20 offset1:1
	ds_read2_b32 v[22:23], v22 offset1:1
	ds_read2_b32 v[24:25], v24 offset1:1
	ds_read2_b32 v[26:27], v70 offset1:1
	ds_read2_b32 v[28:29], v70 offset0:2 offset1:3
	ds_read2_b32 v[30:31], v70 offset0:4 offset1:5
	ds_read2_b32 v[32:33], v70 offset0:6 offset1:7
	ds_read2_b32 v[34:35], v34 offset1:1
	ds_read2_b32 v[36:37], v36 offset1:1
	ds_read2_b32 v[38:39], v38 offset1:1
	ds_read2_b32 v[40:41], v40 offset1:1
	ds_read2_b32 v[42:43], v71 offset1:1
	ds_read2_b32 v[44:45], v72 offset1:1
	ds_read2_b32 v[46:47], v73 offset1:1
	ds_read2_b32 v[48:49], v74 offset1:1
	ds_read2_b32 v[50:51], v75 offset1:1
	ds_read2_b32 v[52:53], v76 offset1:1
	ds_read2_b32 v[54:55], v77 offset1:1
	ds_read2_b32 v[56:57], v78 offset1:1
	ds_read2_b32 v[58:59], v79 offset1:1
	ds_read2_b32 v[60:61], v80 offset1:1
	ds_read2_b32 v[62:63], v81 offset1:1
	ds_read2_b32 v[66:67], v82 offset1:1
	ds_read2_b32 v[68:69], v83 offset1:1
	ds_read2_b32 v[124:125], v84 offset1:1
	ds_read2_b32 v[126:127], v85 offset1:1
	ds_read2_b32 v[128:129], v86 offset1:1
	v_add_u32_e32 v8, s30, v197
	v_ashrrev_i32_e32 v9, 31, v8
	v_lshlrev_b64 v[8:9], 12, v[8:9]
	v_lshl_add_u64 v[8:9], s[6:7], 0, v[8:9]
	v_lshl_add_u64 v[8:9], v[8:9], 0, s[0:1]
	v_lshl_add_u64 v[8:9], v[8:9], 0, v[180:181]
	s_add_i32 s29, s29, s96
	s_cmp_ge_i32 s29, s14
	s_waitcnt vmcnt(1) lgkmcnt(14)
	v_pk_add_f32 v[0:1], v[0:1], v[26:27]
	v_pk_add_f32 v[2:3], v[2:3], v[28:29]
	v_pk_add_f32 v[0:1], v[0:1], v[10:11]
	v_pk_add_f32 v[2:3], v[2:3], v[16:17]
	v_pk_add_f32 v[0:1], v[0:1], v[12:13]
	v_pk_add_f32 v[2:3], v[2:3], v[18:19]
	v_pk_add_f32 v[0:1], v[0:1], v[14:15]
	v_pk_add_f32 v[2:3], v[2:3], v[20:21]
	v_pk_add_f32 v[0:1], v[0:1], v[42:43]
	v_pk_add_f32 v[2:3], v[2:3], v[44:45]
	s_waitcnt lgkmcnt(11)
	v_pk_add_f32 v[0:1], v[0:1], v[50:51]
	s_waitcnt lgkmcnt(10)
	v_pk_add_f32 v[2:3], v[2:3], v[52:53]
	s_waitcnt lgkmcnt(7)
	v_pk_add_f32 v[0:1], v[0:1], v[58:59]
	s_waitcnt lgkmcnt(6)
	v_pk_add_f32 v[2:3], v[2:3], v[60:61]
	s_waitcnt lgkmcnt(3)
	v_pk_add_f32 v[0:1], v[0:1], v[68:69]
	s_waitcnt lgkmcnt(2)
	v_pk_add_f32 v[2:3], v[2:3], v[124:125]
	s_waitcnt vmcnt(0)
	v_pk_add_f32 v[4:5], v[4:5], v[30:31]
	global_store_dwordx4 v[8:9], v[0:3], off
	v_pk_add_f32 v[4:5], v[4:5], v[22:23]
	s_nop 0
	v_pk_add_f32 v[2:3], v[6:7], v[32:33]
	v_pk_add_f32 v[4:5], v[4:5], v[24:25]
	v_pk_add_f32 v[2:3], v[2:3], v[36:37]
	v_pk_add_f32 v[4:5], v[4:5], v[34:35]
	v_pk_add_f32 v[2:3], v[2:3], v[38:39]
	v_pk_add_f32 v[4:5], v[4:5], v[46:47]
	v_pk_add_f32 v[2:3], v[2:3], v[40:41]
	v_pk_add_f32 v[0:1], v[4:5], v[54:55]
	v_pk_add_f32 v[2:3], v[2:3], v[48:49]
	v_pk_add_f32 v[0:1], v[0:1], v[62:63]
	v_pk_add_f32 v[2:3], v[2:3], v[56:57]
	s_waitcnt lgkmcnt(1)
	v_pk_add_f32 v[0:1], v[0:1], v[126:127]
	v_pk_add_f32 v[2:3], v[2:3], v[66:67]
	s_waitcnt lgkmcnt(0)
	v_pk_add_f32 v[2:3], v[2:3], v[128:129]
	global_store_dwordx4 v[8:9], v[0:3], off offset:16
	s_barrier
	s_cbranch_scc0 .LBB0_726

; template <int NH>
; __device__ void gemm_sample_rows(const Params& p, const u16* __restrict__ A, const u16* __restrict__ Bt,
;                                  const float* __restrict__ resid, float* __restrict__ outf, unsigned char* smem, const int rep) {
;     ...
; #pragma unroll 2
;     for (int ks = 0; ks < 8; ++ks) {
;       bf16x8 af[4], bfr[4];
; #pragma unroll
;       for (int mf = 0; mf < 4; ++mf) af[mf] = *(const bf16x8*)(ap + (size_t)(mf * 16) * K + ks * 32);
; #pragma unroll
;       for (int nf = 0; nf < 4; ++nf) bfr[nf] = *(const bf16x8*)(bp + (size_t)(nf * 16) * K + ks * 32);
; #pragma unroll
;       for (int mf = 0; mf < 4; ++mf)
; #pragma unroll
;         for (int nf = 0; nf < 4; ++nf)
;           acc[mf][nf] = __builtin_amdgcn_mfma_f32_16x16x32_bf16(af[mf], bfr[nf], acc[mf][nf], 0, 0, 0);
;     }
.LBB0_2035:
	v_add_co_u32_e64 v200, s[2:3], s18, v68
	s_nop 1
	v_addc_co_u32_e64 v201, s[2:3], 0, v69, s[2:3]
	v_add_co_u32_e64 v202, s[2:3], s19, v68
	s_nop 1
	v_addc_co_u32_e64 v203, s[2:3], 0, v69, s[2:3]
	v_add_co_u32_e64 v204, s[2:3], s20, v68
	s_nop 1
	v_addc_co_u32_e64 v205, s[2:3], 0, v69, s[2:3]
	v_add_co_u32_e64 v206, s[2:3], s21, v68
	s_nop 1
	v_addc_co_u32_e64 v207, s[2:3], 0, v69, s[2:3]
	v_add_co_u32_e64 v208, s[2:3], s22, v70
	s_nop 1
	v_addc_co_u32_e64 v209, s[2:3], 0, v71, s[2:3]
	v_add_co_u32_e64 v210, s[2:3], s23, v70
	s_nop 1
	v_addc_co_u32_e64 v211, s[2:3], 0, v71, s[2:3]
	v_add_co_u32_e64 v212, s[2:3], s24, v70
	s_nop 1
	v_addc_co_u32_e64 v213, s[2:3], 0, v71, s[2:3]
	v_add_co_u32_e64 v214, s[2:3], s25, v70
	s_nop 1
	v_addc_co_u32_e64 v215, s[2:3], 0, v71, s[2:3]
	global_load_dwordx4 v[124:127], v[200:201], off
	global_load_dwordx4 v[128:131], v[202:203], off
	global_load_dwordx4 v[132:135], v[204:205], off
	global_load_dwordx4 v[136:139], v[206:207], off
	global_load_dwordx4 v[140:143], v[208:209], off
	global_load_dwordx4 v[144:147], v[210:211], off
	global_load_dwordx4 v[148:151], v[212:213], off
	global_load_dwordx4 v[152:155], v[214:215], off
	global_load_dwordx4 v[216:219], v[200:201], off offset:64
	global_load_dwordx4 v[220:223], v[202:203], off offset:64
	global_load_dwordx4 v[224:227], v[204:205], off offset:64
	global_load_dwordx4 v[228:231], v[206:207], off offset:64
	global_load_dwordx4 v[232:235], v[208:209], off offset:64
	global_load_dwordx4 v[236:239], v[210:211], off offset:64
	global_load_dwordx4 v[240:243], v[212:213], off offset:64
	global_load_dwordx4 v[244:247], v[214:215], off offset:64
	global_load_dwordx4 v[156:159], v[200:201], off offset:128
	global_load_dwordx4 v[160:163], v[202:203], off offset:128
	global_load_dwordx4 v[164:167], v[204:205], off offset:128
	global_load_dwordx4 v[168:171], v[206:207], off offset:128
	global_load_dwordx4 v[172:175], v[208:209], off offset:128
	global_load_dwordx4 v[176:179], v[210:211], off offset:128
	global_load_dwordx4 v[182:185], v[212:213], off offset:128
	global_load_dwordx4 v[186:189], v[214:215], off offset:128
	s_waitcnt vmcnt(16)
	v_mfma_f32_16x16x32_bf16 v[60:63], v[124:127], v[140:143], v[60:63]
	v_mfma_f32_16x16x32_bf16 v[56:59], v[124:127], v[144:147], v[56:59]
	v_mfma_f32_16x16x32_bf16 v[48:51], v[124:127], v[148:151], v[48:51]
	v_mfma_f32_16x16x32_bf16 v[44:47], v[124:127], v[152:155], v[44:47]
	v_mfma_f32_16x16x32_bf16 v[40:43], v[128:131], v[140:143], v[40:43]
	v_mfma_f32_16x16x32_bf16 v[36:39], v[128:131], v[144:147], v[36:39]
	v_mfma_f32_16x16x32_bf16 v[20:23], v[128:131], v[148:151], v[20:23]
	v_mfma_f32_16x16x32_bf16 v[12:15], v[128:131], v[152:155], v[12:15]
	v_mfma_f32_16x16x32_bf16 v[16:19], v[132:135], v[140:143], v[16:19]
	v_mfma_f32_16x16x32_bf16 v[24:27], v[132:135], v[144:147], v[24:27]
	v_mfma_f32_16x16x32_bf16 v[28:31], v[132:135], v[148:151], v[28:31]
	v_mfma_f32_16x16x32_bf16 v[32:35], v[132:135], v[152:155], v[32:35]
	v_mfma_f32_16x16x32_bf16 v[0:3], v[136:139], v[140:143], v[0:3]
	v_mfma_f32_16x16x32_bf16 v[4:7], v[136:139], v[144:147], v[4:7]
	v_mfma_f32_16x16x32_bf16 v[8:11], v[136:139], v[148:151], v[8:11]
	v_mfma_f32_16x16x32_bf16 v[52:55], v[136:139], v[152:155], v[52:55]
	global_load_dwordx4 v[124:127], v[200:201], off offset:192
	global_load_dwordx4 v[128:131], v[202:203], off offset:192
	global_load_dwordx4 v[132:135], v[204:205], off offset:192
	global_load_dwordx4 v[136:139], v[206:207], off offset:192
	global_load_dwordx4 v[140:143], v[208:209], off offset:192
	global_load_dwordx4 v[144:147], v[210:211], off offset:192
	global_load_dwordx4 v[148:151], v[212:213], off offset:192
	global_load_dwordx4 v[152:155], v[214:215], off offset:192
	s_waitcnt vmcnt(16)
	v_mfma_f32_16x16x32_bf16 v[60:63], v[216:219], v[232:235], v[60:63]
	v_mfma_f32_16x16x32_bf16 v[56:59], v[216:219], v[236:239], v[56:59]
	v_mfma_f32_16x16x32_bf16 v[48:51], v[216:219], v[240:243], v[48:51]
	v_mfma_f32_16x16x32_bf16 v[44:47], v[216:219], v[244:247], v[44:47]
	v_mfma_f32_16x16x32_bf16 v[40:43], v[220:223], v[232:235], v[40:43]
	v_mfma_f32_16x16x32_bf16 v[36:39], v[220:223], v[236:239], v[36:39]
	v_mfma_f32_16x16x32_bf16 v[20:23], v[220:223], v[240:243], v[20:23]
	v_mfma_f32_16x16x32_bf16 v[12:15], v[220:223], v[244:247], v[12:15]
	v_mfma_f32_16x16x32_bf16 v[16:19], v[224:227], v[232:235], v[16:19]
	v_mfma_f32_16x16x32_bf16 v[24:27], v[224:227], v[236:239], v[24:27]
	v_mfma_f32_16x16x32_bf16 v[28:31], v[224:227], v[240:243], v[28:31]
	v_mfma_f32_16x16x32_bf16 v[32:35], v[224:227], v[244:247], v[32:35]
	v_mfma_f32_16x16x32_bf16 v[0:3], v[228:231], v[232:235], v[0:3]
	v_mfma_f32_16x16x32_bf16 v[4:7], v[228:231], v[236:239], v[4:7]
	v_mfma_f32_16x16x32_bf16 v[8:11], v[228:231], v[240:243], v[8:11]
	v_mfma_f32_16x16x32_bf16 v[52:55], v[228:231], v[244:247], v[52:55]
	global_load_dwordx4 v[216:219], v[200:201], off offset:256
	global_load_dwordx4 v[220:223], v[202:203], off offset:256
	global_load_dwordx4 v[224:227], v[204:205], off offset:256
	global_load_dwordx4 v[228:231], v[206:207], off offset:256
	global_load_dwordx4 v[232:235], v[208:209], off offset:256
	global_load_dwordx4 v[236:239], v[210:211], off offset:256
	global_load_dwordx4 v[240:243], v[212:213], off offset:256
	global_load_dwordx4 v[244:247], v[214:215], off offset:256
	s_waitcnt vmcnt(16)
; template <int NH>
; __device__ void gemm_sample_rows(const Params& p, const u16* __restrict__ A, const u16* __restrict__ Bt,
;                                  const float* __restrict__ resid, float* __restrict__ outf, unsigned char* smem, const int rep) {
;     ...
; #pragma unroll 2
;     for (int ks = 0; ks < 8; ++ks) {
;       bf16x8 af[4], bfr[4];
; #pragma unroll
;       for (int mf = 0; mf < 4; ++mf) af[mf] = *(const bf16x8*)(ap + (size_t)(mf * 16) * K + ks * 32);
; #pragma unroll
;       for (int nf = 0; nf < 4; ++nf) bfr[nf] = *(const bf16x8*)(bp + (size_t)(nf * 16) * K + ks * 32);
; #pragma unroll
;       for (int mf = 0; mf < 4; ++mf)
; #pragma unroll
;         for (int nf = 0; nf < 4; ++nf)
;           acc[mf][nf] = __builtin_amdgcn_mfma_f32_16x16x32_bf16(af[mf], bfr[nf], acc[mf][nf], 0, 0, 0);
;     }
	v_mfma_f32_16x16x32_bf16 v[60:63], v[156:159], v[172:175], v[60:63]
	v_mfma_f32_16x16x32_bf16 v[56:59], v[156:159], v[176:179], v[56:59]
	v_mfma_f32_16x16x32_bf16 v[48:51], v[156:159], v[182:185], v[48:51]
	v_mfma_f32_16x16x32_bf16 v[44:47], v[156:159], v[186:189], v[44:47]
	v_mfma_f32_16x16x32_bf16 v[40:43], v[160:163], v[172:175], v[40:43]
	v_mfma_f32_16x16x32_bf16 v[36:39], v[160:163], v[176:179], v[36:39]
	v_mfma_f32_16x16x32_bf16 v[20:23], v[160:163], v[182:185], v[20:23]
	v_mfma_f32_16x16x32_bf16 v[12:15], v[160:163], v[186:189], v[12:15]
	v_mfma_f32_16x16x32_bf16 v[16:19], v[164:167], v[172:175], v[16:19]
	v_mfma_f32_16x16x32_bf16 v[24:27], v[164:167], v[176:179], v[24:27]
	v_mfma_f32_16x16x32_bf16 v[28:31], v[164:167], v[182:185], v[28:31]
	v_mfma_f32_16x16x32_bf16 v[32:35], v[164:167], v[186:189], v[32:35]
	v_mfma_f32_16x16x32_bf16 v[0:3], v[168:171], v[172:175], v[0:3]
	v_mfma_f32_16x16x32_bf16 v[4:7], v[168:171], v[176:179], v[4:7]
	v_mfma_f32_16x16x32_bf16 v[8:11], v[168:171], v[182:185], v[8:11]
	v_mfma_f32_16x16x32_bf16 v[52:55], v[168:171], v[186:189], v[52:55]
	global_load_dwordx4 v[156:159], v[200:201], off offset:320
	global_load_dwordx4 v[160:163], v[202:203], off offset:320
	global_load_dwordx4 v[164:167], v[204:205], off offset:320
	global_load_dwordx4 v[168:171], v[206:207], off offset:320
	global_load_dwordx4 v[172:175], v[208:209], off offset:320
	global_load_dwordx4 v[176:179], v[210:211], off offset:320
	global_load_dwordx4 v[182:185], v[212:213], off offset:320
	global_load_dwordx4 v[186:189], v[214:215], off offset:320
	s_waitcnt vmcnt(16)
	v_mfma_f32_16x16x32_bf16 v[60:63], v[124:127], v[140:143], v[60:63]
	v_mfma_f32_16x16x32_bf16 v[56:59], v[124:127], v[144:147], v[56:59]
	v_mfma_f32_16x16x32_bf16 v[48:51], v[124:127], v[148:151], v[48:51]
	v_mfma_f32_16x16x32_bf16 v[44:47], v[124:127], v[152:155], v[44:47]
	v_mfma_f32_16x16x32_bf16 v[40:43], v[128:131], v[140:143], v[40:43]
	v_mfma_f32_16x16x32_bf16 v[36:39], v[128:131], v[144:147], v[36:39]
	v_mfma_f32_16x16x32_bf16 v[20:23], v[128:131], v[148:151], v[20:23]
	v_mfma_f32_16x16x32_bf16 v[12:15], v[128:131], v[152:155], v[12:15]
	v_mfma_f32_16x16x32_bf16 v[16:19], v[132:135], v[140:143], v[16:19]
	v_mfma_f32_16x16x32_bf16 v[24:27], v[132:135], v[144:147], v[24:27]
	v_mfma_f32_16x16x32_bf16 v[28:31], v[132:135], v[148:151], v[28:31]
	v_mfma_f32_16x16x32_bf16 v[32:35], v[132:135], v[152:155], v[32:35]
	v_mfma_f32_16x16x32_bf16 v[0:3], v[136:139], v[140:143], v[0:3]
	v_mfma_f32_16x16x32_bf16 v[4:7], v[136:139], v[144:147], v[4:7]
	v_mfma_f32_16x16x32_bf16 v[8:11], v[136:139], v[148:151], v[8:11]
	v_mfma_f32_16x16x32_bf16 v[52:55], v[136:139], v[152:155], v[52:55]
	global_load_dwordx4 v[124:127], v[200:201], off offset:384
	global_load_dwordx4 v[128:131], v[202:203], off offset:384
	global_load_dwordx4 v[132:135], v[204:205], off offset:384
	global_load_dwordx4 v[136:139], v[206:207], off offset:384
	global_load_dwordx4 v[140:143], v[208:209], off offset:384
	global_load_dwordx4 v[144:147], v[210:211], off offset:384
	global_load_dwordx4 v[148:151], v[212:213], off offset:384
	global_load_dwordx4 v[152:155], v[214:215], off offset:384
	s_waitcnt vmcnt(16)
	v_mfma_f32_16x16x32_bf16 v[60:63], v[216:219], v[232:235], v[60:63]
	v_mfma_f32_16x16x32_bf16 v[56:59], v[216:219], v[236:239], v[56:59]
	v_mfma_f32_16x16x32_bf16 v[48:51], v[216:219], v[240:243], v[48:51]
	v_mfma_f32_16x16x32_bf16 v[44:47], v[216:219], v[244:247], v[44:47]
	v_mfma_f32_16x16x32_bf16 v[40:43], v[220:223], v[232:235], v[40:43]
	v_mfma_f32_16x16x32_bf16 v[36:39], v[220:223], v[236:239], v[36:39]
	v_mfma_f32_16x16x32_bf16 v[20:23], v[220:223], v[240:243], v[20:23]
	v_mfma_f32_16x16x32_bf16 v[12:15], v[220:223], v[244:247], v[12:15]
	v_mfma_f32_16x16x32_bf16 v[16:19], v[224:227], v[232:235], v[16:19]
	v_mfma_f32_16x16x32_bf16 v[24:27], v[224:227], v[236:239], v[24:27]
	v_mfma_f32_16x16x32_bf16 v[28:31], v[224:227], v[240:243], v[28:31]
	v_mfma_f32_16x16x32_bf16 v[32:35], v[224:227], v[244:247], v[32:35]
	v_mfma_f32_16x16x32_bf16 v[0:3], v[228:231], v[232:235], v[0:3]
	v_mfma_f32_16x16x32_bf16 v[4:7], v[228:231], v[236:239], v[4:7]
	v_mfma_f32_16x16x32_bf16 v[8:11], v[228:231], v[240:243], v[8:11]
	v_mfma_f32_16x16x32_bf16 v[52:55], v[228:231], v[244:247], v[52:55]
	global_load_dwordx4 v[216:219], v[200:201], off offset:448
	global_load_dwordx4 v[220:223], v[202:203], off offset:448
	global_load_dwordx4 v[224:227], v[204:205], off offset:448
	global_load_dwordx4 v[228:231], v[206:207], off offset:448
	global_load_dwordx4 v[232:235], v[208:209], off offset:448
	global_load_dwordx4 v[236:239], v[210:211], off offset:448
	global_load_dwordx4 v[240:243], v[212:213], off offset:448
	global_load_dwordx4 v[244:247], v[214:215], off offset:448
	s_waitcnt vmcnt(16)
	v_mfma_f32_16x16x32_bf16 v[60:63], v[156:159], v[172:175], v[60:63]
	v_mfma_f32_16x16x32_bf16 v[56:59], v[156:159], v[176:179], v[56:59]
	v_mfma_f32_16x16x32_bf16 v[48:51], v[156:159], v[182:185], v[48:51]
	v_mfma_f32_16x16x32_bf16 v[44:47], v[156:159], v[186:189], v[44:47]
	v_mfma_f32_16x16x32_bf16 v[40:43], v[160:163], v[172:175], v[40:43]
	v_mfma_f32_16x16x32_bf16 v[36:39], v[160:163], v[176:179], v[36:39]
	v_mfma_f32_16x16x32_bf16 v[20:23], v[160:163], v[182:185], v[20:23]
	v_mfma_f32_16x16x32_bf16 v[12:15], v[160:163], v[186:189], v[12:15]
	v_mfma_f32_16x16x32_bf16 v[16:19], v[164:167], v[172:175], v[16:19]
	v_mfma_f32_16x16x32_bf16 v[24:27], v[164:167], v[176:179], v[24:27]
	v_mfma_f32_16x16x32_bf16 v[28:31], v[164:167], v[182:185], v[28:31]
	v_mfma_f32_16x16x32_bf16 v[32:35], v[164:167], v[186:189], v[32:35]
	v_mfma_f32_16x16x32_bf16 v[0:3], v[168:171], v[172:175], v[0:3]
	v_mfma_f32_16x16x32_bf16 v[4:7], v[168:171], v[176:179], v[4:7]
	v_mfma_f32_16x16x32_bf16 v[8:11], v[168:171], v[182:185], v[8:11]
	v_mfma_f32_16x16x32_bf16 v[52:55], v[168:171], v[186:189], v[52:55]
	s_waitcnt vmcnt(8)
; template <int NH>
; __device__ void gemm_sample_rows(const Params& p, const u16* __restrict__ A, const u16* __restrict__ Bt,
;                                  const float* __restrict__ resid, float* __restrict__ outf, unsigned char* smem, const int rep) {
;     ...
;       for (int mf = 0; mf < 4; ++mf) af[mf] = *(const bf16x8*)(ap + (size_t)(mf * 16) * K + ks * 32);
; #pragma unroll
;       for (int nf = 0; nf < 4; ++nf) bfr[nf] = *(const bf16x8*)(bp + (size_t)(nf * 16) * K + ks * 32);
; #pragma unroll
;       for (int mf = 0; mf < 4; ++mf)
; #pragma unroll
;         for (int nf = 0; nf < 4; ++nf)
;           acc[mf][nf] = __builtin_amdgcn_mfma_f32_16x16x32_bf16(af[mf], bfr[nf], acc[mf][nf], 0, 0, 0);
;     }
;     __syncthreads();
;     {
;       const int h = (w * 256) / (K / NH);
; #pragma unroll
;       for (int mf = 0; mf < 4; ++mf)
; #pragma unroll
;         for (int r = 0; r < 4; ++r) {
;           const int row = mf * 16 + 4 * g + r;
;           const float sc = rstdS[row * NH + h];
; #pragma unroll
;           for (int nf = 0; nf < 4; ++nf) red[(w * 64 + row) * RS + nf * 16 + l15] = acc[mf][nf][r] * sc;
;         }
;     }
;     __syncthreads();
;     {
;       const int row = tid >> 3, c0 = (tid & 7) * 8;
;       float o[8];
;       const size_t gidx = (size_t)(m0 + row) * 1024 + n0 + c0;
;       const float* rp = resid ? resid + gidx : p.x_sample + (size_t)(m0 - NPROMPT + row) * 1024 + n0 + c0;
	v_mfma_f32_16x16x32_bf16 v[60:63], v[124:127], v[140:143], v[60:63]
	v_mfma_f32_16x16x32_bf16 v[56:59], v[124:127], v[144:147], v[56:59]
	v_mfma_f32_16x16x32_bf16 v[48:51], v[124:127], v[148:151], v[48:51]
	v_mfma_f32_16x16x32_bf16 v[44:47], v[124:127], v[152:155], v[44:47]
	v_mfma_f32_16x16x32_bf16 v[40:43], v[128:131], v[140:143], v[40:43]
	v_mfma_f32_16x16x32_bf16 v[36:39], v[128:131], v[144:147], v[36:39]
	v_mfma_f32_16x16x32_bf16 v[20:23], v[128:131], v[148:151], v[20:23]
	v_mfma_f32_16x16x32_bf16 v[12:15], v[128:131], v[152:155], v[12:15]
	v_mfma_f32_16x16x32_bf16 v[16:19], v[132:135], v[140:143], v[16:19]
	v_mfma_f32_16x16x32_bf16 v[24:27], v[132:135], v[144:147], v[24:27]
	v_mfma_f32_16x16x32_bf16 v[28:31], v[132:135], v[148:151], v[28:31]
	v_mfma_f32_16x16x32_bf16 v[32:35], v[132:135], v[152:155], v[32:35]
	v_mfma_f32_16x16x32_bf16 v[0:3], v[136:139], v[140:143], v[0:3]
	v_mfma_f32_16x16x32_bf16 v[4:7], v[136:139], v[144:147], v[4:7]
	v_mfma_f32_16x16x32_bf16 v[8:11], v[136:139], v[148:151], v[8:11]
	v_mfma_f32_16x16x32_bf16 v[52:55], v[136:139], v[152:155], v[52:55]
	s_waitcnt vmcnt(0)
	v_mfma_f32_16x16x32_bf16 v[60:63], v[216:219], v[232:235], v[60:63]
	v_mfma_f32_16x16x32_bf16 v[56:59], v[216:219], v[236:239], v[56:59]
	v_mfma_f32_16x16x32_bf16 v[48:51], v[216:219], v[240:243], v[48:51]
	v_mfma_f32_16x16x32_bf16 v[44:47], v[216:219], v[244:247], v[44:47]
	v_mfma_f32_16x16x32_bf16 v[40:43], v[220:223], v[232:235], v[40:43]
	v_mfma_f32_16x16x32_bf16 v[36:39], v[220:223], v[236:239], v[36:39]
	v_mfma_f32_16x16x32_bf16 v[20:23], v[220:223], v[240:243], v[20:23]
	v_mfma_f32_16x16x32_bf16 v[12:15], v[220:223], v[244:247], v[12:15]
	v_mfma_f32_16x16x32_bf16 v[16:19], v[224:227], v[232:235], v[16:19]
	v_mfma_f32_16x16x32_bf16 v[24:27], v[224:227], v[236:239], v[24:27]
	v_mfma_f32_16x16x32_bf16 v[28:31], v[224:227], v[240:243], v[28:31]
	v_mfma_f32_16x16x32_bf16 v[32:35], v[224:227], v[244:247], v[32:35]
	v_mfma_f32_16x16x32_bf16 v[0:3], v[228:231], v[232:235], v[0:3]
	v_mfma_f32_16x16x32_bf16 v[4:7], v[228:231], v[236:239], v[4:7]
	v_mfma_f32_16x16x32_bf16 v[8:11], v[228:231], v[240:243], v[8:11]
	v_mfma_f32_16x16x32_bf16 v[52:55], v[228:231], v[244:247], v[52:55]
	s_movk_i32 s0, 0x200
	s_mov_b32 s1, 0
	s_waitcnt lgkmcnt(0)
	s_barrier
	ds_read_b32 v68, v91
	s_lshl_b32 s0, s26, 6
	s_and_b32 s0, s0, 0x3c0
	s_add_i32 s26, s26, s96
	s_add_i32 s13, s13, s14
	s_waitcnt lgkmcnt(0)
	v_mul_f32_e32 v60, v60, v68
	v_mul_f32_e32 v56, v56, v68
	v_mul_f32_e32 v48, v48, v68
	v_mul_f32_e32 v44, v44, v68
	ds_write2_b32 v92, v60, v56 offset1:16
	ds_write2_b32 v92, v48, v44 offset0:32 offset1:48
	ds_read_b32 v44, v93
	s_add_i32 s15, s15, s16
	s_cmp_ge_i32 s26, s12
	s_waitcnt lgkmcnt(0)
	v_mul_f32_e32 v48, v61, v44
	v_mul_f32_e32 v56, v57, v44
	ds_write2_b32 v94, v48, v56 offset1:16
	v_mul_f32_e32 v48, v49, v44
	v_mul_f32_e32 v44, v45, v44
	ds_write2_b32 v94, v48, v44 offset0:32 offset1:48
	ds_read_b32 v44, v95
	s_waitcnt lgkmcnt(0)
	v_mul_f32_e32 v45, v62, v44
	v_mul_f32_e32 v48, v58, v44
	ds_write2_b32 v96, v45, v48 offset1:16
	v_mul_f32_e32 v45, v50, v44
	v_mul_f32_e32 v44, v46, v44
	ds_write2_b32 v96, v45, v44 offset0:32 offset1:48
	ds_read_b32 v44, v97
	s_waitcnt lgkmcnt(0)
	v_mul_f32_e32 v45, v63, v44
	v_mul_f32_e32 v46, v59, v44
	ds_write2_b32 v98, v45, v46 offset1:16
	v_mul_f32_e32 v45, v51, v44
	v_mul_f32_e32 v44, v47, v44
	ds_write2_b32 v98, v45, v44 offset0:32 offset1:48
	ds_read_b32 v44, v99
	s_waitcnt lgkmcnt(0)
	v_mul_f32_e32 v40, v40, v44
	v_mul_f32_e32 v36, v36, v44
	v_mul_f32_e32 v20, v20, v44
	v_mul_f32_e32 v12, v12, v44
	ds_write2_b32 v100, v40, v36 offset1:16
	ds_write2_b32 v100, v20, v12 offset0:32 offset1:48
	ds_read_b32 v12, v101
	v_add_u32_e32 v40, 0xc318, v65
	s_waitcnt lgkmcnt(0)
	v_mul_f32_e32 v20, v41, v12
	v_mul_f32_e32 v36, v37, v12
	ds_write2_b32 v102, v20, v36 offset1:16
	v_mul_f32_e32 v20, v21, v12
	v_mul_f32_e32 v12, v13, v12
	ds_write2_b32 v102, v20, v12 offset0:32 offset1:48
	ds_read_b32 v12, v103
	v_add_u32_e32 v36, 0x4118, v65
	s_waitcnt lgkmcnt(0)
	v_mul_f32_e32 v13, v42, v12
	v_mul_f32_e32 v20, v38, v12
	ds_write2_b32 v104, v13, v20 offset1:16
	v_mul_f32_e32 v13, v22, v12
	v_mul_f32_e32 v12, v14, v12
	ds_write2_b32 v104, v13, v12 offset0:32 offset1:48
	ds_read_b32 v12, v105
	v_add_u32_e32 v20, 0xc308, v65
	v_add_u32_e32 v22, 0x4110, v65
	v_add_u32_e32 v38, 0x8218, v65
	s_waitcnt lgkmcnt(0)
	v_mul_f32_e32 v13, v43, v12
	v_mul_f32_e32 v14, v39, v12
	ds_write2_b32 v106, v13, v14 offset1:16
	v_mul_f32_e32 v13, v23, v12
	v_mul_f32_e32 v12, v15, v12
	ds_write2_b32 v106, v13, v12 offset0:32 offset1:48
	ds_read_b32 v12, v107
	s_waitcnt lgkmcnt(0)
	v_mul_f32_e32 v13, v16, v12
	v_mul_f32_e32 v14, v24, v12
	ds_write2_b32 v108, v13, v14 offset1:16
	v_mul_f32_e32 v13, v28, v12
	v_mul_f32_e32 v12, v32, v12
	ds_write2_b32 v108, v13, v12 offset0:32 offset1:48
	ds_read_b32 v12, v109
	v_add_u32_e32 v16, 0x4108, v65
	v_add_u32_e32 v24, 0x8210, v65
	s_waitcnt lgkmcnt(0)
	v_mul_f32_e32 v13, v17, v12
	v_mul_f32_e32 v14, v25, v12
	ds_write2_b32 v110, v13, v14 offset1:16
	v_mul_f32_e32 v13, v29, v12
	v_mul_f32_e32 v12, v33, v12
	ds_write2_b32 v110, v13, v12 offset0:32 offset1:48
	ds_read_b32 v12, v111
	s_waitcnt lgkmcnt(0)
	v_mul_f32_e32 v13, v18, v12
	v_mul_f32_e32 v14, v26, v12
	ds_write2_b32 v112, v13, v14 offset1:16
	v_mul_f32_e32 v13, v30, v12
	v_mul_f32_e32 v12, v34, v12
	ds_write2_b32 v112, v13, v12 offset0:32 offset1:48
	ds_read_b32 v12, v113
	v_add_u32_e32 v18, 0x8208, v65
	v_add_u32_e32 v34, 0xc310, v65
	s_waitcnt lgkmcnt(0)
	v_mul_f32_e32 v13, v19, v12
	v_mul_f32_e32 v14, v27, v12
	ds_write2_b32 v114, v13, v14 offset1:16
	v_mul_f32_e32 v13, v31, v12
	v_mul_f32_e32 v12, v35, v12
	ds_write2_b32 v114, v13, v12 offset0:32 offset1:48
	ds_read_b32 v12, v115
	v_add_u32_e32 v14, 0xc300, v65
	s_waitcnt lgkmcnt(0)
	v_mul_f32_e32 v0, v0, v12
	v_mul_f32_e32 v4, v4, v12
	ds_write2_b32 v116, v0, v4 offset1:16
	v_mul_f32_e32 v0, v8, v12
	v_mul_f32_e32 v4, v52, v12
	ds_write2_b32 v116, v0, v4 offset0:32 offset1:48
	ds_read_b32 v0, v117
	v_add_u32_e32 v12, 0x8200, v65
	s_waitcnt lgkmcnt(0)
	v_mul_f32_e32 v1, v1, v0
	v_mul_f32_e32 v4, v5, v0
	ds_write2_b32 v118, v1, v4 offset1:16
	v_mul_f32_e32 v1, v9, v0
	v_mul_f32_e32 v0, v53, v0
	ds_write2_b32 v118, v1, v0 offset0:32 offset1:48
	ds_read_b32 v0, v119
	s_waitcnt lgkmcnt(0)
	v_mul_f32_e32 v1, v2, v0
	v_mul_f32_e32 v2, v6, v0
	ds_write2_b32 v120, v1, v2 offset1:16
	v_mul_f32_e32 v1, v10, v0
	v_mul_f32_e32 v0, v54, v0
	ds_write2_b32 v120, v1, v0 offset0:32 offset1:48
	ds_read_b32 v0, v121
	s_waitcnt lgkmcnt(0)
	v_mul_f32_e32 v1, v3, v0
	v_mul_f32_e32 v2, v7, v0
	ds_write2_b32 v122, v1, v2 offset1:16
	v_mul_f32_e32 v1, v11, v0
	v_mul_f32_e32 v0, v55, v0
	ds_write2_b32 v122, v1, v0 offset0:32 offset1:48
	v_add_u32_e32 v0, s27, v197
	v_ashrrev_i32_e32 v1, 31, v0
	v_lshlrev_b64 v[0:1], 10, v[0:1]
	v_or_b32_e32 v0, s0, v0
	v_or_b32_e32 v0, v0, v64
	v_lshlrev_b64 v[8:9], 2, v[0:1]
	v_lshl_add_u64 v[10:11], s[6:7], 0, v[8:9]
	s_waitcnt lgkmcnt(0)
	s_barrier
; template <int NH>
; __device__ void gemm_sample_rows(const Params& p, const u16* __restrict__ A, const u16* __restrict__ Bt,
;                                  const float* __restrict__ resid, float* __restrict__ outf, unsigned char* smem, const int rep) {
;     ...
;     {
;       const int row = tid >> 3, c0 = (tid & 7) * 8;
;       float o[8];
;       const size_t gidx = (size_t)(m0 + row) * 1024 + n0 + c0;
;       const float* rp = resid ? resid + gidx : p.x_sample + (size_t)(m0 - NPROMPT + row) * 1024 + n0 + c0;
;       const float4 r0 = *(const float4*)rp, r1 = *(const float4*)(rp + 4);
;       o[0] = r0.x; o[1] = r0.y; o[2] = r0.z; o[3] = r0.w; o[4] = r1.x; o[5] = r1.y; o[6] = r1.z; o[7] = r1.w;
; #pragma unroll
;       for (int ww = 0; ww < 8; ++ww)
; #pragma unroll
;         for (int j = 0; j < 8; ++j) o[j] += red[(ww * 64 + row) * RS + c0 + j];
;       *(float4*)(outf + gidx) = make_float4(o[0], o[1], o[2], o[3]);
;       *(float4*)(outf + gidx + 4) = make_float4(o[4], o[5], o[6], o[7]);
;     }
;     __syncthreads();
	global_load_dwordx4 v[0:3], v[10:11], off
	global_load_dwordx4 v[4:7], v[10:11], off offset:16
	v_add_u32_e32 v10, 0x4100, v65
	ds_read2_b32 v[10:11], v10 offset1:1
	ds_read2_b32 v[12:13], v12 offset1:1
	ds_read2_b32 v[14:15], v14 offset1:1
	ds_read2_b32 v[16:17], v16 offset1:1
	ds_read2_b32 v[18:19], v18 offset1:1
	ds_read2_b32 v[20:21], v20 offset1:1
	ds_read2_b32 v[22:23], v22 offset1:1
	ds_read2_b32 v[24:25], v24 offset1:1
	ds_read2_b32 v[26:27], v65 offset1:1
	ds_read2_b32 v[28:29], v65 offset0:2 offset1:3
	ds_read2_b32 v[30:31], v65 offset0:4 offset1:5
	ds_read2_b32 v[32:33], v65 offset0:6 offset1:7
	ds_read2_b32 v[34:35], v34 offset1:1
	ds_read2_b32 v[36:37], v36 offset1:1
	ds_read2_b32 v[38:39], v38 offset1:1
	ds_read2_b32 v[40:41], v40 offset1:1
	ds_read2_b32 v[42:43], v72 offset1:1
	ds_read2_b32 v[44:45], v73 offset1:1
	ds_read2_b32 v[46:47], v74 offset1:1
	ds_read2_b32 v[48:49], v75 offset1:1
	ds_read2_b32 v[50:51], v76 offset1:1
	ds_read2_b32 v[52:53], v77 offset1:1
	ds_read2_b32 v[54:55], v78 offset1:1
	ds_read2_b32 v[56:57], v79 offset1:1
	ds_read2_b32 v[58:59], v80 offset1:1
	ds_read2_b32 v[60:61], v81 offset1:1
	ds_read2_b32 v[62:63], v82 offset1:1
	ds_read2_b32 v[68:69], v83 offset1:1
	ds_read2_b32 v[70:71], v84 offset1:1
	ds_read2_b32 v[124:125], v85 offset1:1
	ds_read2_b32 v[126:127], v86 offset1:1
	ds_read2_b32 v[128:129], v87 offset1:1
	v_lshl_add_u64 v[8:9], s[8:9], 0, v[8:9]
	s_waitcnt vmcnt(1) lgkmcnt(14)
	v_pk_add_f32 v[0:1], v[0:1], v[26:27]
	v_pk_add_f32 v[2:3], v[2:3], v[28:29]
	v_pk_add_f32 v[0:1], v[0:1], v[10:11]
	v_pk_add_f32 v[2:3], v[2:3], v[16:17]
	v_pk_add_f32 v[0:1], v[0:1], v[12:13]
	v_pk_add_f32 v[2:3], v[2:3], v[18:19]
	v_pk_add_f32 v[0:1], v[0:1], v[14:15]
	v_pk_add_f32 v[2:3], v[2:3], v[20:21]
	v_pk_add_f32 v[0:1], v[0:1], v[42:43]
	v_pk_add_f32 v[2:3], v[2:3], v[44:45]
	s_waitcnt lgkmcnt(11)
	v_pk_add_f32 v[0:1], v[0:1], v[50:51]
	s_waitcnt lgkmcnt(10)
	v_pk_add_f32 v[2:3], v[2:3], v[52:53]
	s_waitcnt lgkmcnt(7)
	v_pk_add_f32 v[0:1], v[0:1], v[58:59]
	s_waitcnt lgkmcnt(6)
	v_pk_add_f32 v[2:3], v[2:3], v[60:61]
	s_waitcnt vmcnt(0)
	v_pk_add_f32 v[4:5], v[4:5], v[30:31]
	v_pk_add_f32 v[6:7], v[6:7], v[32:33]
	s_waitcnt lgkmcnt(3)
	v_pk_add_f32 v[0:1], v[0:1], v[70:71]
	s_waitcnt lgkmcnt(2)
	v_pk_add_f32 v[2:3], v[2:3], v[124:125]
	v_pk_add_f32 v[4:5], v[4:5], v[22:23]
	global_store_dwordx4 v[8:9], v[0:3], off
	v_pk_add_f32 v[4:5], v[4:5], v[24:25]
	s_nop 0
	v_pk_add_f32 v[0:1], v[6:7], v[36:37]
	v_pk_add_f32 v[4:5], v[4:5], v[34:35]
	v_pk_add_f32 v[0:1], v[0:1], v[38:39]
	v_pk_add_f32 v[4:5], v[4:5], v[46:47]
	v_pk_add_f32 v[0:1], v[0:1], v[40:41]
	v_pk_add_f32 v[4:5], v[4:5], v[54:55]
	v_pk_add_f32 v[0:1], v[0:1], v[48:49]
	v_pk_add_f32 v[4:5], v[4:5], v[62:63]
	v_pk_add_f32 v[0:1], v[0:1], v[56:57]
	s_waitcnt lgkmcnt(1)
	v_pk_add_f32 v[4:5], v[4:5], v[126:127]
	v_pk_add_f32 v[0:1], v[0:1], v[68:69]
	s_waitcnt lgkmcnt(0)
	v_pk_add_f32 v[6:7], v[0:1], v[128:129]
	global_store_dwordx4 v[8:9], v[4:7], off offset:16
	s_barrier
	s_cbranch_scc0 .LBB0_2031
